# attention main loop rewritten as software-pipelined 32-key half-tile loop (PV/softmax/QK overlapped), P packed in place
# speedup vs baseline: 1.0327x; 1.0327x over previous
; #define LAS __attribute__((address_space(3)))
; #define DMAT(kt, so) do { const unsigned rb_ = (unsigned)ROWBASE(kt); _Pragma("unroll") for (int r = 0; r < 3; ++r) if (wid + 8 * r < 22) \
;         __builtin_amdgcn_global_load_lds((const unsigned*)(dsrc[r] + (size_t)rb_ * dmul[r]), (LAS unsigned*)(lds + (so) + dlds[r]), 16, 0, 0); } while (0)
; __device__ __forceinline__ void attn_unit2(LAS unsigned char* lds, const bf16_t* __restrict__ Q, const bf16_t* __restrict__ KN, const bf16_t* __restrict__ KPE, ...
;     ...
;     __syncthreads();
;     int sc = 0, sn = SLOT, snn = 2 * SLOT;
;     f32x16 oa0 = {}, oa1 = {}, ob0 = {}, ob1 = {};
;     float ma = -1.0e30f, mb = -1.0e30f, la = 0.f, lb = 0.f;
;     for (int t = 0; t < ntiles; ++t) {
;         __builtin_amdgcn_sched_barrier(0);
;         f32x16 sa0 = {}, sa1 = {}, sb0 = {}, sb1 = {};
;         const LAS unsigned char* ka = lds + sc + ka_off;
; #pragma unroll
;         for (int ds = 0; ds < 6; ++ds) {
;             const bf16x8 k0 = *(const LAS bf16x8*)(ka + ds * 32);
;             const bf16x8 k1 = *(const LAS bf16x8*)(ka + 32 * KROW + ds * 32);
;             sa0 = __builtin_amdgcn_mfma_f32_32x32x16_bf16(k0, qa[ds], sa0, 0, 0, 0);
;             sa1 = __builtin_amdgcn_mfma_f32_32x32x16_bf16(k1, qa[ds], sa1, 0, 0, 0);
;             sb0 = __builtin_amdgcn_mfma_f32_32x32x16_bf16(k0, qb[ds], sb0, 0, 0, 0);
;             sb1 = __builtin_amdgcn_mfma_f32_32x32x16_bf16(k1, qb[ds], sb1, 0, 0, 0);
;         }
;         __builtin_amdgcn_sched_barrier(0);
;         if (t + 2 < ntiles) DMAT(t + 2, snn);
;         u32x4 pa[4], pb[4];
.LBB0_354:
	v_and_b32_e32 v0, 19, v3
	v_lshlrev_b32_e32 v1, 1, v3
	v_lshrrev_b32_e32 v3, 1, v3
	v_and_b32_e32 v1, 8, v1
	v_and_b32_e32 v3, 4, v3
	v_or3_b32 v0, v0, v1, v3
	v_mov_b32_e32 v16, v129
	v_mov_b32_e32 v17, v129
	v_mov_b32_e32 v30, v129
	v_mov_b32_e32 v31, v129
	v_mul_u32_u24_e32 v183, 0xd0, v0
	v_mul_u32_u24_e32 v187, 0x90, v2
	v_mov_b32_e32 v18, v129
	v_mov_b32_e32 v19, v129
	v_mov_b32_e32 v20, v129
	v_mov_b32_e32 v21, v129
	v_mov_b32_e32 v22, v129
	v_mov_b32_e32 v23, v129
	v_mov_b32_e32 v24, v129
	v_mov_b32_e32 v25, v129
	v_mov_b32_e32 v26, v129
	v_mov_b32_e32 v27, v129
	v_mov_b32_e32 v28, v129
	v_mov_b32_e32 v29, v129
	v_mov_b64_e32 v[62:63], v[30:31]
	v_mov_b64_e32 v[46:47], v[30:31]
	v_mov_b64_e32 v[0:1], v[16:17]
	s_add_i32 s10, s14, 0x4080
	s_add_i32 s11, s24, 0xffffff80
	s_mov_b32 s24, 0
	v_mov_b32_e32 v191, 0
	v_mov_b32_e32 v194, 0xf149f2ca
	s_mov_b32 s25, 0xb000
	s_movk_i32 s26, 0x5800
	s_mov_b32 s14, 0
	v_mov_b64_e32 v[60:61], v[28:29]
	v_mov_b64_e32 v[58:59], v[26:27]
	v_mov_b64_e32 v[56:57], v[24:25]
	v_mov_b64_e32 v[54:55], v[22:23]
	v_mov_b64_e32 v[52:53], v[20:21]
	v_mov_b64_e32 v[50:51], v[18:19]
	v_mov_b64_e32 v[48:49], v[16:17]
	v_mov_b64_e32 v[44:45], v[28:29]
	v_mov_b64_e32 v[42:43], v[26:27]
	v_mov_b64_e32 v[40:41], v[24:25]
	v_mov_b64_e32 v[38:39], v[22:23]
	v_mov_b64_e32 v[36:37], v[20:21]
	v_mov_b64_e32 v[34:35], v[18:19]
	v_mov_b64_e32 v[32:33], v[16:17]
	v_mov_b64_e32 v[2:3], v[18:19]
	v_mov_b64_e32 v[4:5], v[20:21]
	v_mov_b64_e32 v[6:7], v[22:23]
	v_mov_b64_e32 v[8:9], v[24:25]
	v_mov_b64_e32 v[10:11], v[26:27]
	v_mov_b64_e32 v[12:13], v[28:29]
	v_mov_b64_e32 v[14:15], v[30:31]
	v_mov_b32_e32 v195, 0xf149f2ca
	v_mov_b32_e32 v193, 0
	s_mov_b32 s27, 0
	s_waitcnt vmcnt(0) lgkmcnt(0)
	s_barrier
	s_mov_b32 s34, s14
	v_mov_b32_e32 v96, 0
	v_mov_b32_e32 v97, 0
	v_mov_b32_e32 v98, 0
	v_mov_b32_e32 v99, 0
	v_mov_b32_e32 v100, 0
	v_mov_b32_e32 v101, 0
	v_mov_b32_e32 v102, 0
	v_mov_b32_e32 v103, 0
	v_mov_b32_e32 v112, 0
	v_mov_b32_e32 v113, 0
	v_mov_b32_e32 v114, 0
	v_mov_b32_e32 v115, 0
	v_mov_b32_e32 v116, 0
	v_mov_b32_e32 v117, 0
	v_mov_b32_e32 v118, 0
	v_mov_b32_e32 v119, 0
	v_add3_u32 v224, s34, v183, v128
	ds_read_b128 v[212:215], v224 offset:0
	ds_read_b128 v[216:219], v224 offset:32
	ds_read_b128 v[220:223], v224 offset:64
	s_waitcnt lgkmcnt(2)
	v_mfma_f32_32x32x16_bf16 v[64:79], v[212:215], v[130:133], 0
	v_mfma_f32_32x32x16_bf16 v[80:95], v[212:215], v[138:141], 0
	ds_read_b128 v[212:215], v224 offset:96
	s_waitcnt lgkmcnt(2)
	v_mfma_f32_32x32x16_bf16 v[64:79], v[216:219], v[134:137], v[64:79]
	v_mfma_f32_32x32x16_bf16 v[80:95], v[216:219], v[142:145], v[80:95]
	ds_read_b128 v[216:219], v224 offset:128
	s_waitcnt lgkmcnt(2)
	v_mfma_f32_32x32x16_bf16 v[64:79], v[220:223], v[146:149], v[64:79]
	v_mfma_f32_32x32x16_bf16 v[80:95], v[220:223], v[154:157], v[80:95]
	ds_read_b128 v[220:223], v224 offset:160
	s_waitcnt lgkmcnt(2)
	v_mfma_f32_32x32x16_bf16 v[64:79], v[212:215], v[150:153], v[64:79]
	v_mfma_f32_32x32x16_bf16 v[80:95], v[212:215], v[158:161], v[80:95]
	s_waitcnt lgkmcnt(1)
	v_mfma_f32_32x32x16_bf16 v[64:79], v[216:219], v[162:165], v[64:79]
	v_mfma_f32_32x32x16_bf16 v[80:95], v[216:219], v[170:173], v[80:95]
	s_waitcnt lgkmcnt(0)
	v_mfma_f32_32x32x16_bf16 v[64:79], v[220:223], v[166:169], v[64:79]
	v_mfma_f32_32x32x16_bf16 v[80:95], v[220:223], v[174:177], v[80:95]
	v_add3_u32 v225, s34, v187, v128
	ds_read_b128 v[196:199], v225 offset:13376
	ds_read_b128 v[200:203], v225 offset:17984
	ds_read_b128 v[204:207], v225 offset:13408
	ds_read_b128 v[208:211], v225 offset:18016
	s_nop 7
	s_nop 3
.Lat_loop:
	v_add3_u32 v224, s34, v183, v128
	ds_read_b128 v[212:215], v224 offset:6656
	ds_read_b128 v[216:219], v224 offset:6688
	ds_read_b128 v[220:223], v224 offset:6720
	s_waitcnt lgkmcnt(6)
	v_mfma_f32_32x32x16_bf16 v[16:31], v[196:199], v[96:99], v[16:31]
	v_max3_f32 v226, v64, v65, v66
	v_max3_f32 v227, v67, v68, v69
	v_max3_f32 v226, v226, v70, v71
	s_waitcnt lgkmcnt(5)
	v_mfma_f32_32x32x16_bf16 v[48:63], v[200:203], v[96:99], v[48:63]
	v_max3_f32 v227, v227, v72, v73
	v_max3_f32 v226, v226, v74, v75
	v_max3_f32 v227, v227, v76, v77
	s_waitcnt lgkmcnt(4)
	v_mfma_f32_32x32x16_bf16 v[16:31], v[204:207], v[100:103], v[16:31]
	v_max3_f32 v226, v226, v78, v79
	v_max_f32_e32 v226, v226, v227
	s_waitcnt lgkmcnt(3)
	v_mfma_f32_32x32x16_bf16 v[48:63], v[208:211], v[100:103], v[48:63]
	v_mov_b32_e32 v227, v226
	s_nop 1
	v_permlane32_swap_b32_e32 v226, v227
	v_max_f32_e32 v226, v226, v227
	v_sub_f32_e32 v227, v226, v194
	v_cmp_lt_f32_e32 vcc, s33, v227
	s_cbranch_vccnz .Lat_resc_aE
; #define LAS __attribute__((address_space(3)))
; #define DMAT(kt, so) do { const unsigned rb_ = (unsigned)ROWBASE(kt); _Pragma("unroll") for (int r = 0; r < 3; ++r) if (wid + 8 * r < 22) \
;         __builtin_amdgcn_global_load_lds((const unsigned*)(dsrc[r] + (size_t)rb_ * dmul[r]), (LAS unsigned*)(lds + (so) + dlds[r]), 16, 0, 0); } while (0)
; __device__ __forceinline__ void attn_unit2(LAS unsigned char* lds, const bf16_t* __restrict__ Q, const bf16_t* __restrict__ KN, const bf16_t* __restrict__ KPE, ...
;     ...
;         f32x16 sa0 = {}, sa1 = {}, sb0 = {}, sb1 = {};
;         const LAS unsigned char* ka = lds + sc + ka_off;
; #pragma unroll
;         for (int ds = 0; ds < 6; ++ds) {
;             const bf16x8 k0 = *(const LAS bf16x8*)(ka + ds * 32);
;             const bf16x8 k1 = *(const LAS bf16x8*)(ka + 32 * KROW + ds * 32);
;             sa0 = __builtin_amdgcn_mfma_f32_32x32x16_bf16(k0, qa[ds], sa0, 0, 0, 0);
;             sa1 = __builtin_amdgcn_mfma_f32_32x32x16_bf16(k1, qa[ds], sa1, 0, 0, 0);
;             sb0 = __builtin_amdgcn_mfma_f32_32x32x16_bf16(k0, qb[ds], sb0, 0, 0, 0);
;             sb1 = __builtin_amdgcn_mfma_f32_32x32x16_bf16(k1, qb[ds], sb1, 0, 0, 0);
;         }
;         __builtin_amdgcn_sched_barrier(0);
;         if (t + 2 < ntiles) DMAT(t + 2, snn);
;         u32x4 pa[4], pb[4];
;     ...
;         SOFTMAX2(sa0, sa1, ma, la, oa0, oa1, pa);
;         SOFTMAX2(sb0, sb1, mb, lb, ob0, ob1, pb);
;     ...
;         const LAS unsigned char* va = lds + sc + va_off;
; #pragma unroll
;         for (int st = 0; st < 4; ++st) {
;             const bf16x8 v0 = *(const LAS bf16x8*)(va + st * 32);
;             const bf16x8 v1 = *(const LAS bf16x8*)(va + 32 * VROW + st * 32);
;             const bf16x8 fa = __builtin_bit_cast(bf16x8, pa[st]), fb = __builtin_bit_cast(bf16x8, pb[st]);
;             oa0 = __builtin_amdgcn_mfma_f32_32x32x16_bf16(v0, fa, oa0, 0, 0, 0);
;             oa1 = __builtin_amdgcn_mfma_f32_32x32x16_bf16(v1, fa, oa1, 0, 0, 0);
;             ob0 = __builtin_amdgcn_mfma_f32_32x32x16_bf16(v0, fb, ob0, 0, 0, 0);
;             ob1 = __builtin_amdgcn_mfma_f32_32x32x16_bf16(v1, fb, ob1, 0, 0, 0);
.Lat_back_aE:
	v_mfma_f32_32x32x16_bf16 v[32:47], v[196:199], v[112:115], v[32:47]
	v_sub_f32_e32 v64, v64, v194
	v_sub_f32_e32 v65, v65, v194
	v_sub_f32_e32 v66, v66, v194
	v_sub_f32_e32 v67, v67, v194
	v_exp_f32_e32 v64, v64
	v_mfma_f32_32x32x16_bf16 v[0:15], v[200:203], v[112:115], v[0:15]
	v_exp_f32_e32 v65, v65
	v_sub_f32_e32 v68, v68, v194
	v_sub_f32_e32 v69, v69, v194
	v_exp_f32_e32 v66, v66
	v_exp_f32_e32 v67, v67
	v_mfma_f32_32x32x16_bf16 v[32:47], v[204:207], v[116:119], v[32:47]
	v_sub_f32_e32 v70, v70, v194
	v_sub_f32_e32 v71, v71, v194
	v_exp_f32_e32 v68, v68
	v_exp_f32_e32 v69, v69
	v_add_f32_e32 v230, v64, v65
	v_mfma_f32_32x32x16_bf16 v[0:15], v[208:211], v[116:119], v[0:15]
	v_sub_f32_e32 v72, v72, v194
	v_sub_f32_e32 v73, v73, v194
	v_add3_u32 v225, s34, v187, v128
	ds_read_b128 v[196:199], v225 offset:13312
	ds_read_b128 v[200:203], v225 offset:17920
	ds_read_b128 v[204:207], v225 offset:13344
	ds_read_b128 v[208:211], v225 offset:17952
	v_exp_f32_e32 v70, v70
	v_exp_f32_e32 v71, v71
	v_add_f32_e32 v231, v66, v67
	v_sub_f32_e32 v74, v74, v194
	s_waitcnt lgkmcnt(6)
	v_mfma_f32_32x32x16_bf16 v[96:111], v[212:215], v[130:133], 0
	v_sub_f32_e32 v75, v75, v194
	v_exp_f32_e32 v72, v72
	v_exp_f32_e32 v73, v73
	v_add_f32_e32 v230, v230, v68
	v_add_f32_e32 v231, v231, v69
	v_sub_f32_e32 v76, v76, v194
	v_sub_f32_e32 v77, v77, v194
	v_mfma_f32_32x32x16_bf16 v[112:127], v[212:215], v[138:141], 0
	ds_read_b128 v[212:215], v224 offset:6752
	v_exp_f32_e32 v74, v74
	v_exp_f32_e32 v75, v75
	v_add_f32_e32 v230, v230, v70
	v_add_f32_e32 v231, v231, v71
	v_sub_f32_e32 v78, v78, v194
	v_sub_f32_e32 v79, v79, v194
	v_exp_f32_e32 v76, v76
	v_exp_f32_e32 v77, v77
	s_waitcnt lgkmcnt(6)
	v_mfma_f32_32x32x16_bf16 v[96:111], v[216:219], v[134:137], v[96:111]
	v_add_f32_e32 v230, v230, v72
	v_add_f32_e32 v231, v231, v73
	v_exp_f32_e32 v78, v78
	v_exp_f32_e32 v79, v79
	v_add_f32_e32 v230, v230, v74
	v_add_f32_e32 v231, v231, v75
	v_add_f32_e32 v230, v230, v76
	v_mfma_f32_32x32x16_bf16 v[112:127], v[216:219], v[142:145], v[112:127]
	ds_read_b128 v[216:219], v224 offset:6784
	v_add_f32_e32 v231, v231, v77
	v_add_f32_e32 v230, v230, v78
	v_add_f32_e32 v231, v231, v79
	v_add_f32_e32 v230, v230, v231
	v_add_f32_e32 v191, v191, v230
	v_cvt_pk_bf16_f32 v64, v64, v65
	v_cvt_pk_bf16_f32 v65, v66, v67
	s_waitcnt lgkmcnt(6)
	v_mfma_f32_32x32x16_bf16 v[96:111], v[220:223], v[146:149], v[96:111]
	v_cvt_pk_bf16_f32 v66, v68, v69
	v_cvt_pk_bf16_f32 v67, v70, v71
	v_cvt_pk_bf16_f32 v68, v72, v73
	v_cvt_pk_bf16_f32 v69, v74, v75
	v_cvt_pk_bf16_f32 v70, v76, v77
	v_cvt_pk_bf16_f32 v71, v78, v79
	v_max3_f32 v228, v80, v81, v82
	v_max3_f32 v229, v83, v84, v85
	v_mfma_f32_32x32x16_bf16 v[112:127], v[220:223], v[154:157], v[112:127]
	ds_read_b128 v[220:223], v224 offset:6816
	v_max3_f32 v228, v228, v86, v87
	v_max3_f32 v229, v229, v88, v89
	v_max3_f32 v228, v228, v90, v91
	v_max3_f32 v229, v229, v92, v93
	v_max3_f32 v228, v228, v94, v95
	v_max_f32_e32 v228, v228, v229
	v_mov_b32_e32 v229, v228
	s_waitcnt lgkmcnt(2)
	v_mfma_f32_32x32x16_bf16 v[96:111], v[212:215], v[150:153], v[96:111]
	s_nop 1
	v_permlane32_swap_b32_e32 v228, v229
	v_max_f32_e32 v228, v228, v229
	v_sub_f32_e32 v229, v228, v195
	v_cmp_lt_f32_e32 vcc, s33, v229
	s_cbranch_vccnz .Lat_resc_bE
.Lat_back_bE:
	v_sub_f32_e32 v80, v80, v195
	v_sub_f32_e32 v81, v81, v195
	v_sub_f32_e32 v82, v82, v195
	v_mfma_f32_32x32x16_bf16 v[112:127], v[212:215], v[158:161], v[112:127]
	v_sub_f32_e32 v83, v83, v195
	v_exp_f32_e32 v80, v80
	v_exp_f32_e32 v81, v81
	v_sub_f32_e32 v84, v84, v195
	v_sub_f32_e32 v85, v85, v195
	v_exp_f32_e32 v82, v82
	v_exp_f32_e32 v83, v83
	s_waitcnt lgkmcnt(1)
	v_mfma_f32_32x32x16_bf16 v[96:111], v[216:219], v[162:165], v[96:111]
	v_sub_f32_e32 v86, v86, v195
	v_sub_f32_e32 v87, v87, v195
	v_exp_f32_e32 v84, v84
	v_exp_f32_e32 v85, v85
	v_add_f32_e32 v236, v80, v81
	v_sub_f32_e32 v88, v88, v195
	v_sub_f32_e32 v89, v89, v195
	v_mfma_f32_32x32x16_bf16 v[112:127], v[216:219], v[170:173], v[112:127]
	v_exp_f32_e32 v86, v86
	v_exp_f32_e32 v87, v87
	v_add_f32_e32 v237, v82, v83
	v_sub_f32_e32 v90, v90, v195
	v_sub_f32_e32 v91, v91, v195
	v_exp_f32_e32 v88, v88
	v_exp_f32_e32 v89, v89
	v_add_f32_e32 v236, v236, v84
	s_waitcnt lgkmcnt(0)
	v_mfma_f32_32x32x16_bf16 v[96:111], v[220:223], v[166:169], v[96:111]
	v_add_f32_e32 v237, v237, v85
	v_sub_f32_e32 v92, v92, v195
	v_sub_f32_e32 v93, v93, v195
	v_exp_f32_e32 v90, v90
	v_exp_f32_e32 v91, v91
	v_add_f32_e32 v236, v236, v86
	v_add_f32_e32 v237, v237, v87
	v_mfma_f32_32x32x16_bf16 v[112:127], v[220:223], v[174:177], v[112:127]
	v_sub_f32_e32 v94, v94, v195
	v_sub_f32_e32 v95, v95, v195
	v_exp_f32_e32 v92, v92
	v_exp_f32_e32 v93, v93
	v_add_f32_e32 v236, v236, v88
	v_add_f32_e32 v237, v237, v89
	v_exp_f32_e32 v94, v94
	v_exp_f32_e32 v95, v95
	v_add_f32_e32 v236, v236, v90
	v_add_f32_e32 v237, v237, v91
	v_add_f32_e32 v236, v236, v92
	v_add_f32_e32 v237, v237, v93
	v_add_f32_e32 v236, v236, v94
	v_add_f32_e32 v237, v237, v95
	v_add_f32_e32 v236, v236, v237
	v_add_f32_e32 v193, v193, v236
	v_cvt_pk_bf16_f32 v80, v80, v81
	v_cvt_pk_bf16_f32 v81, v82, v83
	v_cvt_pk_bf16_f32 v82, v84, v85
	v_cvt_pk_bf16_f32 v83, v86, v87
	v_cvt_pk_bf16_f32 v84, v88, v89
	v_cvt_pk_bf16_f32 v85, v90, v91
	v_cvt_pk_bf16_f32 v86, v92, v93
	v_cvt_pk_bf16_f32 v87, v94, v95
	s_waitcnt vmcnt(0)
	s_barrier
	s_cmpk_gt_u32 s27, 0x81
	s_cbranch_scc1 .Lat_dma_endL
	s_cmp_lt_u32 s27, 2
	s_cselect_b32 s14, s10, s11
	s_add_i32 s14, s14, s24
	s_and_b64 vcc, exec, s[4:5]
	s_cbranch_vccnz .Lat_dmaL_0
	v_mad_u64_u32 v[234:235], s[16:17], v182, s14, v[180:181]
	s_add_i32 m0, s25, s19
	s_nop 0
	global_load_lds_dwordx4 v[234:235], off
; #define LAS __attribute__((address_space(3)))
; __device__ __forceinline__ void attn_unit2(LAS unsigned char* lds, const bf16_t* __restrict__ Q, const bf16_t* __restrict__ KN, const bf16_t* __restrict__ KPE, ...
;     ...
;     DMAT(0, 0);
;     DMAT(1, SLOT);
;     __syncthreads();
;     int sc = 0, sn = SLOT, snn = 2 * SLOT;
;     f32x16 oa0 = {}, oa1 = {}, ob0 = {}, ob1 = {};
;     float ma = -1.0e30f, mb = -1.0e30f, la = 0.f, lb = 0.f;
;     for (int t = 0; t < ntiles; ++t) {
;         __builtin_amdgcn_sched_barrier(0);
;         f32x16 sa0 = {}, sa1 = {}, sb0 = {}, sb1 = {};
;         const LAS unsigned char* ka = lds + sc + ka_off;
; #pragma unroll
;         for (int ds = 0; ds < 6; ++ds) {
;             const bf16x8 k0 = *(const LAS bf16x8*)(ka + ds * 32);
;             const bf16x8 k1 = *(const LAS bf16x8*)(ka + 32 * KROW + ds * 32);
;             sa0 = __builtin_amdgcn_mfma_f32_32x32x16_bf16(k0, qa[ds], sa0, 0, 0, 0);
;             sa1 = __builtin_amdgcn_mfma_f32_32x32x16_bf16(k1, qa[ds], sa1, 0, 0, 0);
;             sb0 = __builtin_amdgcn_mfma_f32_32x32x16_bf16(k0, qb[ds], sb0, 0, 0, 0);
;             sb1 = __builtin_amdgcn_mfma_f32_32x32x16_bf16(k1, qb[ds], sb1, 0, 0, 0);
;         }
;         __builtin_amdgcn_sched_barrier(0);
;         if (t + 2 < ntiles) DMAT(t + 2, snn);
;         u32x4 pa[4], pb[4];
;     ...
;         SOFTMAX2(sa0, sa1, ma, la, oa0, oa1, pa);
;         SOFTMAX2(sb0, sb1, mb, lb, ob0, ob1, pb);
;     ...
;         const LAS unsigned char* va = lds + sc + va_off;
; #pragma unroll
;         for (int st = 0; st < 4; ++st) {
;             const bf16x8 v0 = *(const LAS bf16x8*)(va + st * 32);
;             const bf16x8 v1 = *(const LAS bf16x8*)(va + 32 * VROW + st * 32);
;             const bf16x8 fa = __builtin_bit_cast(bf16x8, pa[st]), fb = __builtin_bit_cast(bf16x8, pb[st]);
;             oa0 = __builtin_amdgcn_mfma_f32_32x32x16_bf16(v0, fa, oa0, 0, 0, 0);
;             oa1 = __builtin_amdgcn_mfma_f32_32x32x16_bf16(v1, fa, oa1, 0, 0, 0);
;             ob0 = __builtin_amdgcn_mfma_f32_32x32x16_bf16(v0, fb, ob0, 0, 0, 0);
;             ob1 = __builtin_amdgcn_mfma_f32_32x32x16_bf16(v1, fb, ob1, 0, 0, 0);
.Lat_dmaL_0:
	s_and_b64 vcc, exec, s[6:7]
	s_cbranch_vccnz .Lat_dmaL_1
	v_mad_u64_u32 v[234:235], s[16:17], v186, s14, v[184:185]
	s_add_i32 m0, s25, s20
	s_nop 0
	global_load_lds_dwordx4 v[234:235], off
.Lat_dmaL_1:
	s_and_b64 vcc, exec, s[8:9]
	s_cbranch_vccnz .Lat_dmaL_2
	v_mad_u64_u32 v[234:235], s[16:17], v190, s14, v[188:189]
	s_add_i32 m0, s25, s21
	s_nop 0
	global_load_lds_dwordx4 v[234:235], off
.Lat_dmaL_2:
.Lat_dma_endL:
	v_add3_u32 v224, s26, v183, v128
	ds_read_b128 v[212:215], v224 offset:0
	ds_read_b128 v[216:219], v224 offset:32
	ds_read_b128 v[220:223], v224 offset:64
	v_mfma_f32_32x32x16_bf16 v[16:31], v[196:199], v[64:67], v[16:31]
	v_max3_f32 v226, v96, v97, v98
	v_max3_f32 v227, v99, v100, v101
	v_max3_f32 v226, v226, v102, v103
	v_mfma_f32_32x32x16_bf16 v[48:63], v[200:203], v[64:67], v[48:63]
	v_max3_f32 v227, v227, v104, v105
	v_max3_f32 v226, v226, v106, v107
	v_max3_f32 v227, v227, v108, v109
	v_mfma_f32_32x32x16_bf16 v[16:31], v[204:207], v[68:71], v[16:31]
	v_max3_f32 v226, v226, v110, v111
	v_max_f32_e32 v226, v226, v227
	v_mfma_f32_32x32x16_bf16 v[48:63], v[208:211], v[68:71], v[48:63]
	v_mov_b32_e32 v227, v226
	s_nop 1
	v_permlane32_swap_b32_e32 v226, v227
	v_max_f32_e32 v226, v226, v227
	v_sub_f32_e32 v227, v226, v194
	v_cmp_lt_f32_e32 vcc, s33, v227
	s_cbranch_vccnz .Lat_resc_aO
.Lat_back_aO:
	v_mfma_f32_32x32x16_bf16 v[32:47], v[196:199], v[80:83], v[32:47]
	v_sub_f32_e32 v96, v96, v194
	v_sub_f32_e32 v97, v97, v194
	v_sub_f32_e32 v98, v98, v194
	v_sub_f32_e32 v99, v99, v194
	v_exp_f32_e32 v96, v96
	v_mfma_f32_32x32x16_bf16 v[0:15], v[200:203], v[80:83], v[0:15]
	v_exp_f32_e32 v97, v97
	v_sub_f32_e32 v100, v100, v194
	v_sub_f32_e32 v101, v101, v194
	v_exp_f32_e32 v98, v98
	v_exp_f32_e32 v99, v99
	v_mfma_f32_32x32x16_bf16 v[32:47], v[204:207], v[84:87], v[32:47]
	v_sub_f32_e32 v102, v102, v194
	v_sub_f32_e32 v103, v103, v194
	v_exp_f32_e32 v100, v100
	v_exp_f32_e32 v101, v101
	v_add_f32_e32 v230, v96, v97
	v_mfma_f32_32x32x16_bf16 v[0:15], v[208:211], v[84:87], v[0:15]
	v_sub_f32_e32 v104, v104, v194
	v_sub_f32_e32 v105, v105, v194
	v_add3_u32 v225, s34, v187, v128
	ds_read_b128 v[196:199], v225 offset:13376
	ds_read_b128 v[200:203], v225 offset:17984
	ds_read_b128 v[204:207], v225 offset:13408
	ds_read_b128 v[208:211], v225 offset:18016
	v_exp_f32_e32 v102, v102
	v_exp_f32_e32 v103, v103
	v_add_f32_e32 v231, v98, v99
	v_sub_f32_e32 v106, v106, v194
	s_waitcnt lgkmcnt(6)
	v_mfma_f32_32x32x16_bf16 v[64:79], v[212:215], v[130:133], 0
	v_sub_f32_e32 v107, v107, v194
	v_exp_f32_e32 v104, v104
	v_exp_f32_e32 v105, v105
	v_add_f32_e32 v230, v230, v100
	v_add_f32_e32 v231, v231, v101
	v_sub_f32_e32 v108, v108, v194
	v_sub_f32_e32 v109, v109, v194
	v_mfma_f32_32x32x16_bf16 v[80:95], v[212:215], v[138:141], 0
	ds_read_b128 v[212:215], v224 offset:96
	v_exp_f32_e32 v106, v106
	v_exp_f32_e32 v107, v107
	v_add_f32_e32 v230, v230, v102
	v_add_f32_e32 v231, v231, v103
	v_sub_f32_e32 v110, v110, v194
	v_sub_f32_e32 v111, v111, v194
	v_exp_f32_e32 v108, v108
	v_exp_f32_e32 v109, v109
	s_waitcnt lgkmcnt(6)
	v_mfma_f32_32x32x16_bf16 v[64:79], v[216:219], v[134:137], v[64:79]
	v_add_f32_e32 v230, v230, v104
	v_add_f32_e32 v231, v231, v105
	v_exp_f32_e32 v110, v110
	v_exp_f32_e32 v111, v111
	v_add_f32_e32 v230, v230, v106
	v_add_f32_e32 v231, v231, v107
	v_add_f32_e32 v230, v230, v108
	v_mfma_f32_32x32x16_bf16 v[80:95], v[216:219], v[142:145], v[80:95]
	ds_read_b128 v[216:219], v224 offset:128
	v_add_f32_e32 v231, v231, v109
	v_add_f32_e32 v230, v230, v110
	v_add_f32_e32 v231, v231, v111
	v_add_f32_e32 v230, v230, v231
	v_add_f32_e32 v191, v191, v230
	v_cvt_pk_bf16_f32 v96, v96, v97
	v_cvt_pk_bf16_f32 v97, v98, v99
	s_waitcnt lgkmcnt(6)
	v_mfma_f32_32x32x16_bf16 v[64:79], v[220:223], v[146:149], v[64:79]
	v_cvt_pk_bf16_f32 v98, v100, v101
	v_cvt_pk_bf16_f32 v99, v102, v103
	v_cvt_pk_bf16_f32 v100, v104, v105
	v_cvt_pk_bf16_f32 v101, v106, v107
	v_cvt_pk_bf16_f32 v102, v108, v109
	v_cvt_pk_bf16_f32 v103, v110, v111
	v_max3_f32 v228, v112, v113, v114
	v_max3_f32 v229, v115, v116, v117
	v_mfma_f32_32x32x16_bf16 v[80:95], v[220:223], v[154:157], v[80:95]
	ds_read_b128 v[220:223], v224 offset:160
	v_max3_f32 v228, v228, v118, v119
	v_max3_f32 v229, v229, v120, v121
	v_max3_f32 v228, v228, v122, v123
	v_max3_f32 v229, v229, v124, v125
	v_max3_f32 v228, v228, v126, v127
	v_max_f32_e32 v228, v228, v229
	v_mov_b32_e32 v229, v228
	s_waitcnt lgkmcnt(2)
	v_mfma_f32_32x32x16_bf16 v[64:79], v[212:215], v[150:153], v[64:79]
	s_nop 1
	v_permlane32_swap_b32_e32 v228, v229
	v_max_f32_e32 v228, v228, v229
	v_sub_f32_e32 v229, v228, v195
	v_cmp_lt_f32_e32 vcc, s33, v229
	s_cbranch_vccnz .Lat_resc_bO
; #define LAS __attribute__((address_space(3)))
; __device__ __forceinline__ void attn_unit2(LAS unsigned char* lds, const bf16_t* __restrict__ Q, const bf16_t* __restrict__ KN, const bf16_t* __restrict__ KPE, ...
;     ...
;         SOFTMAX2(sa0, sa1, ma, la, oa0, oa1, pa);
;         SOFTMAX2(sb0, sb1, mb, lb, ob0, ob1, pb);
;     ...
;         const LAS unsigned char* va = lds + sc + va_off;
; #pragma unroll
;         for (int st = 0; st < 4; ++st) {
;             const bf16x8 v0 = *(const LAS bf16x8*)(va + st * 32);
;             const bf16x8 v1 = *(const LAS bf16x8*)(va + 32 * VROW + st * 32);
;             const bf16x8 fa = __builtin_bit_cast(bf16x8, pa[st]), fb = __builtin_bit_cast(bf16x8, pb[st]);
;             oa0 = __builtin_amdgcn_mfma_f32_32x32x16_bf16(v0, fa, oa0, 0, 0, 0);
;             oa1 = __builtin_amdgcn_mfma_f32_32x32x16_bf16(v1, fa, oa1, 0, 0, 0);
;             ob0 = __builtin_amdgcn_mfma_f32_32x32x16_bf16(v0, fb, ob0, 0, 0, 0);
;             ob1 = __builtin_amdgcn_mfma_f32_32x32x16_bf16(v1, fb, ob1, 0, 0, 0);
;         }
;         __builtin_amdgcn_sched_barrier(0);
;         __syncthreads();
;         { const int tmp = sc; sc = sn; sn = snn; snn = tmp; }
.Lat_back_bO:
	v_sub_f32_e32 v112, v112, v195
	v_sub_f32_e32 v113, v113, v195
	v_sub_f32_e32 v114, v114, v195
	v_mfma_f32_32x32x16_bf16 v[80:95], v[212:215], v[158:161], v[80:95]
	v_sub_f32_e32 v115, v115, v195
	v_exp_f32_e32 v112, v112
	v_exp_f32_e32 v113, v113
	v_sub_f32_e32 v116, v116, v195
	v_sub_f32_e32 v117, v117, v195
	v_exp_f32_e32 v114, v114
	v_exp_f32_e32 v115, v115
	s_waitcnt lgkmcnt(1)
	v_mfma_f32_32x32x16_bf16 v[64:79], v[216:219], v[162:165], v[64:79]
	v_sub_f32_e32 v118, v118, v195
	v_sub_f32_e32 v119, v119, v195
	v_exp_f32_e32 v116, v116
	v_exp_f32_e32 v117, v117
	v_add_f32_e32 v236, v112, v113
	v_sub_f32_e32 v120, v120, v195
	v_sub_f32_e32 v121, v121, v195
	v_mfma_f32_32x32x16_bf16 v[80:95], v[216:219], v[170:173], v[80:95]
	v_exp_f32_e32 v118, v118
	v_exp_f32_e32 v119, v119
	v_add_f32_e32 v237, v114, v115
	v_sub_f32_e32 v122, v122, v195
	v_sub_f32_e32 v123, v123, v195
	v_exp_f32_e32 v120, v120
	v_exp_f32_e32 v121, v121
	v_add_f32_e32 v236, v236, v116
	s_waitcnt lgkmcnt(0)
	v_mfma_f32_32x32x16_bf16 v[64:79], v[220:223], v[166:169], v[64:79]
	v_add_f32_e32 v237, v237, v117
	v_sub_f32_e32 v124, v124, v195
	v_sub_f32_e32 v125, v125, v195
	v_exp_f32_e32 v122, v122
	v_exp_f32_e32 v123, v123
	v_add_f32_e32 v236, v236, v118
	v_add_f32_e32 v237, v237, v119
	v_mfma_f32_32x32x16_bf16 v[80:95], v[220:223], v[174:177], v[80:95]
	v_sub_f32_e32 v126, v126, v195
	v_sub_f32_e32 v127, v127, v195
	v_exp_f32_e32 v124, v124
	v_exp_f32_e32 v125, v125
	v_add_f32_e32 v236, v236, v120
	v_add_f32_e32 v237, v237, v121
	v_exp_f32_e32 v126, v126
	v_exp_f32_e32 v127, v127
	v_add_f32_e32 v236, v236, v122
	v_add_f32_e32 v237, v237, v123
	v_add_f32_e32 v236, v236, v124
	v_add_f32_e32 v237, v237, v125
	v_add_f32_e32 v236, v236, v126
	v_add_f32_e32 v237, v237, v127
	v_add_f32_e32 v236, v236, v237
	v_add_f32_e32 v193, v193, v236
	v_cvt_pk_bf16_f32 v112, v112, v113
	v_cvt_pk_bf16_f32 v113, v114, v115
	v_cvt_pk_bf16_f32 v114, v116, v117
	v_cvt_pk_bf16_f32 v115, v118, v119
	v_cvt_pk_bf16_f32 v116, v120, v121
	v_cvt_pk_bf16_f32 v117, v122, v123
	v_cvt_pk_bf16_f32 v118, v124, v125
	v_cvt_pk_bf16_f32 v119, v126, v127
	s_add_i32 s27, s27, 1
	s_add_i32 s24, s24, 64
	s_mov_b32 s14, s34
	s_mov_b32 s34, s26
	s_mov_b32 s26, s25
	s_mov_b32 s25, s14
	s_cmpk_lg_i32 s27, 0x84
	s_cbranch_scc1 .Lat_loop
	s_waitcnt lgkmcnt(3)
	v_mfma_f32_32x32x16_bf16 v[16:31], v[196:199], v[96:99], v[16:31]
	s_waitcnt lgkmcnt(2)
	v_mfma_f32_32x32x16_bf16 v[48:63], v[200:203], v[96:99], v[48:63]
	s_waitcnt lgkmcnt(1)
	v_mfma_f32_32x32x16_bf16 v[16:31], v[204:207], v[100:103], v[16:31]
	s_waitcnt lgkmcnt(0)
	v_mfma_f32_32x32x16_bf16 v[48:63], v[208:211], v[100:103], v[48:63]
	v_mfma_f32_32x32x16_bf16 v[32:47], v[196:199], v[112:115], v[32:47]
	v_mfma_f32_32x32x16_bf16 v[0:15], v[200:203], v[112:115], v[0:15]
	v_mfma_f32_32x32x16_bf16 v[32:47], v[204:207], v[116:119], v[32:47]
	v_mfma_f32_32x32x16_bf16 v[0:15], v[208:211], v[116:119], v[0:15]
	s_branch .Lat_done
.Lat_resc_aE:
	s_nop 15
	v_max_f32_e32 v227, v226, v194
	v_sub_f32_e32 v232, v194, v227
	v_exp_f32_e32 v232, v232
	v_mov_b32_e32 v194, v227
	s_nop 0
	v_pk_mul_f32 v[16:17], v[16:17], v[232:233] op_sel_hi:[1,0]
	v_pk_mul_f32 v[18:19], v[18:19], v[232:233] op_sel_hi:[1,0]
	v_pk_mul_f32 v[20:21], v[20:21], v[232:233] op_sel_hi:[1,0]
	v_pk_mul_f32 v[22:23], v[22:23], v[232:233] op_sel_hi:[1,0]
	v_pk_mul_f32 v[24:25], v[24:25], v[232:233] op_sel_hi:[1,0]
	v_pk_mul_f32 v[26:27], v[26:27], v[232:233] op_sel_hi:[1,0]
	v_pk_mul_f32 v[28:29], v[28:29], v[232:233] op_sel_hi:[1,0]
	v_pk_mul_f32 v[30:31], v[30:31], v[232:233] op_sel_hi:[1,0]
	v_pk_mul_f32 v[48:49], v[48:49], v[232:233] op_sel_hi:[1,0]
	v_pk_mul_f32 v[50:51], v[50:51], v[232:233] op_sel_hi:[1,0]
	v_pk_mul_f32 v[52:53], v[52:53], v[232:233] op_sel_hi:[1,0]
	v_pk_mul_f32 v[54:55], v[54:55], v[232:233] op_sel_hi:[1,0]
	v_pk_mul_f32 v[56:57], v[56:57], v[232:233] op_sel_hi:[1,0]
	v_pk_mul_f32 v[58:59], v[58:59], v[232:233] op_sel_hi:[1,0]
	v_pk_mul_f32 v[60:61], v[60:61], v[232:233] op_sel_hi:[1,0]
	v_pk_mul_f32 v[62:63], v[62:63], v[232:233] op_sel_hi:[1,0]
	v_mul_f32_e32 v191, v191, v232
	s_branch .Lat_back_aE
.Lat_resc_bE:
	s_nop 15
	v_max_f32_e32 v229, v228, v195
	v_sub_f32_e32 v232, v195, v229
	v_exp_f32_e32 v232, v232
	v_mov_b32_e32 v195, v229
	s_nop 0
	v_pk_mul_f32 v[32:33], v[32:33], v[232:233] op_sel_hi:[1,0]
	v_pk_mul_f32 v[34:35], v[34:35], v[232:233] op_sel_hi:[1,0]
	v_pk_mul_f32 v[36:37], v[36:37], v[232:233] op_sel_hi:[1,0]
	v_pk_mul_f32 v[38:39], v[38:39], v[232:233] op_sel_hi:[1,0]
	v_pk_mul_f32 v[40:41], v[40:41], v[232:233] op_sel_hi:[1,0]
	v_pk_mul_f32 v[42:43], v[42:43], v[232:233] op_sel_hi:[1,0]
	v_pk_mul_f32 v[44:45], v[44:45], v[232:233] op_sel_hi:[1,0]
	v_pk_mul_f32 v[46:47], v[46:47], v[232:233] op_sel_hi:[1,0]
	v_pk_mul_f32 v[0:1], v[0:1], v[232:233] op_sel_hi:[1,0]
	v_pk_mul_f32 v[2:3], v[2:3], v[232:233] op_sel_hi:[1,0]
	v_pk_mul_f32 v[4:5], v[4:5], v[232:233] op_sel_hi:[1,0]
	v_pk_mul_f32 v[6:7], v[6:7], v[232:233] op_sel_hi:[1,0]
	v_pk_mul_f32 v[8:9], v[8:9], v[232:233] op_sel_hi:[1,0]
	v_pk_mul_f32 v[10:11], v[10:11], v[232:233] op_sel_hi:[1,0]
	v_pk_mul_f32 v[12:13], v[12:13], v[232:233] op_sel_hi:[1,0]
	v_pk_mul_f32 v[14:15], v[14:15], v[232:233] op_sel_hi:[1,0]
	v_mul_f32_e32 v193, v193, v232
	s_branch .Lat_back_bE

; __device__ __forceinline__ unsigned cvt_pk_bf16(float lo, float hi) { const f32x2 v = {lo, hi}; return __builtin_bit_cast(unsigned, __builtin_convertvector(v, bf16x2_t)); }
; __device__ __forceinline__ float xhalf_sum(float m) { auto rr = __builtin_amdgcn_permlane32_swap(__float_as_uint(m), __float_as_uint(m), false, false); return __uint_as_float(rr[0]) + __uint_as_float(rr[1]); }
; __device__ __forceinline__ void attn_unit2(LAS unsigned char* lds, const bf16_t* __restrict__ Q, const bf16_t* __restrict__ KN, const bf16_t* __restrict__ KPE, ...
;     ...
;     const float inva = __builtin_amdgcn_rcpf(xhalf_sum(la)), invb = __builtin_amdgcn_rcpf(xhalf_sum(lb));
;     bf16_t* op = MIX + (size_t)(qrow0 + wid * 64 + r32) * DM + h * 64 + 4 * hi;
; #pragma unroll
;     for (int g = 0; g < 4; ++g) {
;         u32x2 w0, w1;
;         w0.x = cvt_pk_bf16(oa0[4 * g] * inva, oa0[4 * g + 1] * inva); w0.y = cvt_pk_bf16(oa0[4 * g + 2] * inva, oa0[4 * g + 3] * inva);
;         w1.x = cvt_pk_bf16(oa1[4 * g] * inva, oa1[4 * g + 1] * inva); w1.y = cvt_pk_bf16(oa1[4 * g + 2] * inva, oa1[4 * g + 3] * inva);
;         *(u32x2*)(op + 8 * g) = w0; *(u32x2*)(op + 32 + 8 * g) = w1;
;         w0.x = cvt_pk_bf16(ob0[4 * g] * invb, ob0[4 * g + 1] * invb); w0.y = cvt_pk_bf16(ob0[4 * g + 2] * invb, ob0[4 * g + 3] * invb);
;         w1.x = cvt_pk_bf16(ob1[4 * g] * invb, ob1[4 * g + 1] * invb); w1.y = cvt_pk_bf16(ob1[4 * g + 2] * invb, ob1[4 * g + 3] * invb);
;         *(u32x2*)(op + (size_t)32 * DM + 8 * g) = w0; *(u32x2*)(op + (size_t)32 * DM + 32 + 8 * g) = w1;
;     }
.Lat_done:
	s_nop 15
